# mirror of v130: static priority raise for waves 0-3 (instead of 4-7) in the attention j-loop
# baseline (speedup 1.0000x reference)
; #define PROBE_BEGIN(id) unsigned long long pb_t0_##id = 0; if (PROBE_SEC == (id)) pb_t0_##id = __builtin_amdgcn_s_memrealtime();
; #define LAS __attribute__((address_space(3)))
; __device__ __forceinline__ void attn_compute(Frame& F, int id) {
;     const int b = id >> 5, n = (id >> 1) & 15, kvh = id & 1;
;     LAS unsigned char* lds = F.lds;
;     const bf16* Q = (const bf16*)(F.ws + WS_Q); const bf16* ZA = (const bf16*)(F.ws + WS_ZA);
;     bf16* A5 = (bf16*)(F.ws + WS_A5);
;     const float* sink = F.in[4];
;     const int lane = F.lane, wid = F.wave;
;     const int key0 = 128 * (n - 1);
;     PROBE_BEGIN(4)
;     const int g = wid >> 1, qh = wid & 1, h = kvh * 4 + g, r = lane & 31, hh = lane >> 5;
;     const float sk = sink[h] * LOG2E;
;     const size_t tok0 = (size_t)b * SEQ + 128 * n + 64 * qh + r;
;     bf16x8 qf[2][4];
; #pragma unroll
;     for (int qb = 0; qb < 2; ++qb)
; #pragma unroll
;         for (int st = 0; st < 4; ++st) qf[qb][st] = *(const bf16x8*)(Q + (tok0 + 32 * qb) * 512 + h * 64 + 16 * st + 8 * hh);
;     const LAS f32x4* BT4 = (const LAS f32x4*)(lds + OFF_B);
;     const int ktA = 2 * qh;
;     const LAS f32x4* BTg = BT4 + g * NBT + 63 - r + 4 * hh;
;     const LAS unsigned char* kbase = lds + OFF_K + (32 * ktA + r) * KROW + 16 * hh;
;     const LAS unsigned char* vbase = lds + OFF_V + r * VROW + (32 * ktA + 4 * hh) * 2;
;     float m0 = sk, m1 = sk, l0 = 0.f, l1 = 0.f;
;     f32x16 O0[2], O1[2];
; #pragma unroll
;     for (int q = 0; q < 16; ++q) { O0[0][q] = 0.f; O0[1][q] = 0.f; O1[0][q] = 0.f; O1[1][q] = 0.f; }
; #pragma unroll 1
;     for (int j = 0; j < 9; ++j) {
.LBB0_574:
	v_readfirstlane_b32 s4, v0
	s_nop 3
	s_bitcmp1_b32 s4, 8
	s_cbranch_scc1 .Lattn_hi_half
	s_setprio 1
